# prologue: additionally rotate the wave index per layer inside the weight-transpose layer loop (skip flags recomputed) to balance items per wave
# baseline (speedup 1.0000x reference)
; #define TR(Wp, gn_, K_, N_, ldn_, dst_, ldk_, koff_) do { const int nblk_ = (N_) / 32, nit_ = ((K_) / 64) * nblk_; \
;         for (int it = gw; it < nit_; it += ngw) transpose_item((Wp), (gn_), (ldn_), nblk_, (bf16*)(dst_), (ldk_), (koff_), scr, it, lane); } while (0)
; __device__ __forceinline__ void prologue(const Params& p, LAS unsigned char* lds, int gw, int ngw, int wave, int lane) {
;     ...
; #pragma unroll 1
;     for (int l = 0; l < 2; ++l) {
;         unsigned char* wl = ws + W_LAYER + l * WL_SIZE;
;         TR(p.in[I_MWQ] + (size_t)l * 1024 * 512, p.in[I_LNMEM] + l * D, 1024, 512, 512, wl + WL_WQ, 1024, 0);
;         TR(p.in[I_MWKV] + (size_t)l * 1024 * 1024, nog, 1024, 1024, 1024, wl + WL_WKV, 1024, 0);
;         TR(p.in[I_MWO] + (size_t)l * 512 * 1024, nog, 512, 1024, 1024, wl + WL_WO, 512, 0);
;         TR(p.in[I_FWUP] + (size_t)l * 1024 * 2 * DFF, p.in[I_LNFFN] + l * D, 1024, 2 * DFF, 2 * DFF, wl + WL_WUP, 1024, 0);
;         TR(p.in[I_FWDN] + (size_t)l * DFF * 1024, nog, DFF, 1024, 1024, wl + WL_WDN, DFF, 0);
;     }
.LBB0_27:
	s_cmp_lg_u32 s30, 0
	s_cselect_b32 s98, 5, 2
	s_add_u32 s98, s98, s84
	s_and_b32 s98, s98, 7
	s_lshr_b32 s99, s6, 3
	s_mul_i32 s98, s98, s99
	v_readlane_b32 s99, v240, 16
	s_add_u32 s33, s98, s99
	s_cmpk_lt_i32 s33, 0x100
	s_cselect_b64 s[0:1], 0, -1
	s_cmpk_lt_i32 s33, 0x200
	s_cselect_b64 s[4:5], -1, 0
	s_cmpk_lt_i32 s33, 0xb00
	s_cselect_b64 s[20:21], -1, 0
	s_cmpk_lt_i32 s33, 0x580
	s_cselect_b64 s[28:29], -1, 0
	s_nop 0
	s_nop 0
	s_nop 0
	s_nop 0
	s_nop 0
	s_nop 0
	s_nop 0
	s_nop 0
	s_nop 0
	s_nop 0
	s_nop 0
	s_nop 0
	s_nop 0
	s_nop 0
	s_nop 0
	s_mul_i32 s2, s30, 0x1480000
	s_add_u32 s2, s64, s2
	s_addc_u32 s3, s65, 0
	s_and_b64 vcc, exec, s[0:1]
	v_lshl_add_u64 v[14:15], v[2:3], 1, s[2:3]
	s_cbranch_vccnz .LBB0_32
	s_lshl_b64 s[2:3], s[30:31], 21
	s_lshl_b32 s38, s30, 10
	s_mov_b32 s39, s31
	v_lshl_add_u64 v[16:17], v[4:5], 0, s[2:3]
	s_lshl_b64 s[2:3], s[38:39], 2
	s_add_u32 s2, s40, s2
	s_addc_u32 s3, s41, s3
	s_lshl_b32 s46, s33, 5
	s_lshl_b32 s47, s6, 5
	s_mov_b32 s53, s33
	s_branch .LBB0_30

; __global__ void __launch_bounds__(NTHR, 2) fwd_megakernel(Params p) {
	.amdhsa_kernel _Z14fwd_megakernel6Params
		.amdhsa_group_segment_fixed_size 0
		.amdhsa_private_segment_fixed_size 0
		.amdhsa_kernarg_size 544
		.amdhsa_user_sgpr_count 2
		.amdhsa_user_sgpr_dispatch_ptr 0
		.amdhsa_user_sgpr_queue_ptr 0
		.amdhsa_user_sgpr_kernarg_segment_ptr 1
		.amdhsa_user_sgpr_dispatch_id 0
		.amdhsa_user_sgpr_kernarg_preload_length 0
		.amdhsa_user_sgpr_kernarg_preload_offset 0
		.amdhsa_user_sgpr_private_segment_size 0
		.amdhsa_uses_dynamic_stack 0
		.amdhsa_enable_private_segment 0
		.amdhsa_system_sgpr_workgroup_id_x 1
		.amdhsa_system_sgpr_workgroup_id_y 0
		.amdhsa_system_sgpr_workgroup_id_z 0
		.amdhsa_system_sgpr_workgroup_info 0
		.amdhsa_system_vgpr_workitem_id 2
		.amdhsa_next_free_vgpr 241
		.amdhsa_next_free_sgpr 102
		.amdhsa_accum_offset 244
		.amdhsa_reserve_vcc 1
		.amdhsa_float_round_mode_32 0
		.amdhsa_float_round_mode_16_64 0
		.amdhsa_float_denorm_mode_32 3
		.amdhsa_float_denorm_mode_16_64 3
		.amdhsa_dx10_clamp 1
		.amdhsa_ieee_mode 1
		.amdhsa_fp16_overflow 0
		.amdhsa_tg_split 0
		.amdhsa_exception_fp_ieee_invalid_op 0
		.amdhsa_exception_fp_denorm_src 0
		.amdhsa_exception_fp_ieee_div_zero 0
		.amdhsa_exception_fp_ieee_overflow 0
		.amdhsa_exception_fp_ieee_underflow 0
		.amdhsa_exception_fp_ieee_inexact 0
		.amdhsa_exception_int_div_zero 0
	.end_amdhsa_kernel

; __global__ void __launch_bounds__(NTHR, 2) fwd_megakernel(Params p) {
amdhsa.kernels:
  - .agpr_count:     0
    .args:
      - .offset:         0
        .size:           288
        .value_kind:     by_value
      - .offset:         288
        .size:           4
        .value_kind:     hidden_block_count_x
      - .offset:         292
        .size:           4
        .value_kind:     hidden_block_count_y
      - .offset:         296
        .size:           4
        .value_kind:     hidden_block_count_z
      - .offset:         300
        .size:           2
        .value_kind:     hidden_group_size_x
      - .offset:         302
        .size:           2
        .value_kind:     hidden_group_size_y
      - .offset:         304
        .size:           2
        .value_kind:     hidden_group_size_z
      - .offset:         306
        .size:           2
        .value_kind:     hidden_remainder_x
      - .offset:         308
        .size:           2
        .value_kind:     hidden_remainder_y
      - .offset:         310
        .size:           2
        .value_kind:     hidden_remainder_z
      - .offset:         328
        .size:           8
        .value_kind:     hidden_global_offset_x
      - .offset:         336
        .size:           8
        .value_kind:     hidden_global_offset_y
      - .offset:         344
        .size:           8
        .value_kind:     hidden_global_offset_z
      - .offset:         352
        .size:           2
        .value_kind:     hidden_grid_dims
      - .offset:         376
        .size:           8
        .value_kind:     hidden_multigrid_sync_arg
      - .offset:         408
        .size:           4
        .value_kind:     hidden_dynamic_lds_size
    .group_segment_fixed_size: 0
    .kernarg_segment_align: 8
    .kernarg_segment_size: 544
    .language:       OpenCL C
    .language_version:
      - 2
      - 0
    .max_flat_workgroup_size: 512
    .name:           _Z14fwd_megakernel6Params
    .private_segment_fixed_size: 0
    .sgpr_count:     108
    .sgpr_spill_count: 199
    .symbol:         _Z14fwd_megakernel6Params.kd
    .uniform_work_group_size: 1
    .uses_dynamic_stack: false
    .vgpr_count:     241
    .vgpr_spill_count: 0
    .wavefront_size: 64
